# hand-written packed-f32 SwiGLU epilogue (FFN-in GEMM), bit-identical math
# speedup vs baseline: 1.0094x; 1.0094x over previous
.LBB0_667:
	s_cmp_lg_u32 s66, s9
	s_cbranch_scc1 .Lp4_epi_slow
	v_lshl_add_u32 v146, s66, 8, v141
	ds_read_b32 v216, v149
	ds_read_b32 v218, v149 offset:64
	ds_read_b32 v220, v149 offset:128
	ds_read_b32 v222, v149 offset:192
	ds_read_b32 v224, v150
	ds_read_b32 v226, v149 offset:576
	ds_read_b32 v228, v149 offset:640
	ds_read_b32 v230, v149 offset:704
	s_lshl_b32 s6, s14, 7
	s_or_b32 s6, s6, s75
	s_ashr_i32 s10, s6, 6
	s_ashr_i32 s11, s10, 31
	s_lshl_b64 s[14:15], s[10:11], 21
	s_add_u32 s66, s57, s14
	s_addc_u32 s67, s74, s15
	v_lshlrev_b32_e32 v2, 1, v140
	v_lshl_add_u32 v212, v146, 7, v2
	v_add_u32_e32 v213, 0x1000, v212
	v_add_u32_e32 v214, 0x4000, v212
	v_add_u32_e32 v215, 0x5000, v212
	v_mov_b32_e32 v154, 0xbfb8aa3b
	v_mov_b32_e32 v156, 1.0
	s_waitcnt lgkmcnt(0)
	v_pk_mul_f32 v[128:129], v[128:129], v[216:217] op_sel_hi:[1,0]
	v_pk_mul_f32 v[130:131], v[130:131], v[216:217] op_sel_hi:[1,0]
	v_pk_mul_f32 v[120:121], v[120:121], v[216:217] op_sel_hi:[1,0]
	v_pk_mul_f32 v[122:123], v[122:123], v[216:217] op_sel_hi:[1,0]
	v_pk_mul_f32 v[124:125], v[124:125], v[216:217] op_sel_hi:[1,0]
	v_pk_mul_f32 v[126:127], v[126:127], v[216:217] op_sel_hi:[1,0]
	v_pk_mul_f32 v[116:117], v[116:117], v[216:217] op_sel_hi:[1,0]
	v_pk_mul_f32 v[118:119], v[118:119], v[216:217] op_sel_hi:[1,0]
	v_pk_mul_f32 v[200:201], v[128:129], v[154:155] op_sel_hi:[1,0]
	v_pk_mul_f32 v[202:203], v[130:131], v[154:155] op_sel_hi:[1,0]
	v_pk_mul_f32 v[204:205], v[120:121], v[154:155] op_sel_hi:[1,0]
	v_pk_mul_f32 v[206:207], v[122:123], v[154:155] op_sel_hi:[1,0]
	v_exp_f32_e32 v200, v200
	v_exp_f32_e32 v201, v201
	v_exp_f32_e32 v202, v202
	v_exp_f32_e32 v203, v203
	v_exp_f32_e32 v204, v204
	v_exp_f32_e32 v205, v205
	v_exp_f32_e32 v206, v206
	v_exp_f32_e32 v207, v207
	v_pk_add_f32 v[200:201], v[200:201], v[156:157] op_sel_hi:[1,0]
	v_pk_add_f32 v[202:203], v[202:203], v[156:157] op_sel_hi:[1,0]
	v_pk_add_f32 v[204:205], v[204:205], v[156:157] op_sel_hi:[1,0]
	v_pk_add_f32 v[206:207], v[206:207], v[156:157] op_sel_hi:[1,0]
	v_rcp_f32_e32 v200, v200
	v_rcp_f32_e32 v201, v201
	v_rcp_f32_e32 v202, v202
	v_rcp_f32_e32 v203, v203
	v_rcp_f32_e32 v204, v204
	v_rcp_f32_e32 v205, v205
	v_rcp_f32_e32 v206, v206
	v_rcp_f32_e32 v207, v207
	v_pk_mul_f32 v[128:129], v[128:129], v[200:201]
	v_pk_mul_f32 v[130:131], v[130:131], v[202:203]
	v_pk_mul_f32 v[120:121], v[120:121], v[204:205]
	v_pk_mul_f32 v[122:123], v[122:123], v[206:207]
	v_pk_mul_f32 v[128:129], v[128:129], v[124:125]
	v_pk_mul_f32 v[130:131], v[130:131], v[126:127]
	v_pk_mul_f32 v[120:121], v[120:121], v[116:117]
	v_pk_mul_f32 v[122:123], v[122:123], v[118:119]
	v_cvt_pk_bf16_f32 v208, v128, v129
	v_cvt_pk_bf16_f32 v209, v130, v131
	v_cvt_pk_bf16_f32 v210, v120, v121
	v_cvt_pk_bf16_f32 v211, v122, v123
	global_store_dwordx4 v212, v[208:211], s[66:67]
	v_pk_mul_f32 v[112:113], v[112:113], v[218:219] op_sel_hi:[1,0]
	v_pk_mul_f32 v[114:115], v[114:115], v[218:219] op_sel_hi:[1,0]
	v_pk_mul_f32 v[104:105], v[104:105], v[218:219] op_sel_hi:[1,0]
	v_pk_mul_f32 v[106:107], v[106:107], v[218:219] op_sel_hi:[1,0]
	v_pk_mul_f32 v[108:109], v[108:109], v[218:219] op_sel_hi:[1,0]
	v_pk_mul_f32 v[110:111], v[110:111], v[218:219] op_sel_hi:[1,0]
	v_pk_mul_f32 v[100:101], v[100:101], v[218:219] op_sel_hi:[1,0]
	v_pk_mul_f32 v[102:103], v[102:103], v[218:219] op_sel_hi:[1,0]
	v_pk_mul_f32 v[200:201], v[112:113], v[154:155] op_sel_hi:[1,0]
	v_pk_mul_f32 v[202:203], v[114:115], v[154:155] op_sel_hi:[1,0]
	v_pk_mul_f32 v[204:205], v[104:105], v[154:155] op_sel_hi:[1,0]
	v_pk_mul_f32 v[206:207], v[106:107], v[154:155] op_sel_hi:[1,0]
	v_exp_f32_e32 v200, v200
	v_exp_f32_e32 v201, v201
	v_exp_f32_e32 v202, v202
	v_exp_f32_e32 v203, v203
	v_exp_f32_e32 v204, v204
	v_exp_f32_e32 v205, v205
	v_exp_f32_e32 v206, v206
	v_exp_f32_e32 v207, v207
	v_pk_add_f32 v[200:201], v[200:201], v[156:157] op_sel_hi:[1,0]
	v_pk_add_f32 v[202:203], v[202:203], v[156:157] op_sel_hi:[1,0]
	v_pk_add_f32 v[204:205], v[204:205], v[156:157] op_sel_hi:[1,0]
	v_pk_add_f32 v[206:207], v[206:207], v[156:157] op_sel_hi:[1,0]
	v_rcp_f32_e32 v200, v200
	v_rcp_f32_e32 v201, v201
	v_rcp_f32_e32 v202, v202
	v_rcp_f32_e32 v203, v203
	v_rcp_f32_e32 v204, v204
	v_rcp_f32_e32 v205, v205
	v_rcp_f32_e32 v206, v206
	v_rcp_f32_e32 v207, v207
	v_pk_mul_f32 v[112:113], v[112:113], v[200:201]
	v_pk_mul_f32 v[114:115], v[114:115], v[202:203]
	v_pk_mul_f32 v[104:105], v[104:105], v[204:205]
	v_pk_mul_f32 v[106:107], v[106:107], v[206:207]
	v_pk_mul_f32 v[112:113], v[112:113], v[108:109]
	v_pk_mul_f32 v[114:115], v[114:115], v[110:111]
	v_pk_mul_f32 v[104:105], v[104:105], v[100:101]
	v_pk_mul_f32 v[106:107], v[106:107], v[102:103]
	v_cvt_pk_bf16_f32 v208, v112, v113
	v_cvt_pk_bf16_f32 v209, v114, v115
	v_cvt_pk_bf16_f32 v210, v104, v105
	v_cvt_pk_bf16_f32 v211, v106, v107
	global_store_dwordx4 v212, v[208:211], s[66:67] offset:2048
	v_pk_mul_f32 v[96:97], v[96:97], v[220:221] op_sel_hi:[1,0]
	v_pk_mul_f32 v[98:99], v[98:99], v[220:221] op_sel_hi:[1,0]
	v_pk_mul_f32 v[88:89], v[88:89], v[220:221] op_sel_hi:[1,0]
	v_pk_mul_f32 v[90:91], v[90:91], v[220:221] op_sel_hi:[1,0]
	v_pk_mul_f32 v[92:93], v[92:93], v[220:221] op_sel_hi:[1,0]
	v_pk_mul_f32 v[94:95], v[94:95], v[220:221] op_sel_hi:[1,0]
	v_pk_mul_f32 v[84:85], v[84:85], v[220:221] op_sel_hi:[1,0]
	v_pk_mul_f32 v[86:87], v[86:87], v[220:221] op_sel_hi:[1,0]
	v_pk_mul_f32 v[200:201], v[96:97], v[154:155] op_sel_hi:[1,0]
	v_pk_mul_f32 v[202:203], v[98:99], v[154:155] op_sel_hi:[1,0]
	v_pk_mul_f32 v[204:205], v[88:89], v[154:155] op_sel_hi:[1,0]
	v_pk_mul_f32 v[206:207], v[90:91], v[154:155] op_sel_hi:[1,0]
	v_exp_f32_e32 v200, v200
	v_exp_f32_e32 v201, v201
	v_exp_f32_e32 v202, v202
	v_exp_f32_e32 v203, v203
	v_exp_f32_e32 v204, v204
	v_exp_f32_e32 v205, v205
	v_exp_f32_e32 v206, v206
	v_exp_f32_e32 v207, v207
	v_pk_add_f32 v[200:201], v[200:201], v[156:157] op_sel_hi:[1,0]
	v_pk_add_f32 v[202:203], v[202:203], v[156:157] op_sel_hi:[1,0]
	v_pk_add_f32 v[204:205], v[204:205], v[156:157] op_sel_hi:[1,0]
	v_pk_add_f32 v[206:207], v[206:207], v[156:157] op_sel_hi:[1,0]
	v_rcp_f32_e32 v200, v200
	v_rcp_f32_e32 v201, v201
	v_rcp_f32_e32 v202, v202
	v_rcp_f32_e32 v203, v203
	v_rcp_f32_e32 v204, v204
	v_rcp_f32_e32 v205, v205
	v_rcp_f32_e32 v206, v206
	v_rcp_f32_e32 v207, v207
	v_pk_mul_f32 v[96:97], v[96:97], v[200:201]
	v_pk_mul_f32 v[98:99], v[98:99], v[202:203]
	v_pk_mul_f32 v[88:89], v[88:89], v[204:205]
	v_pk_mul_f32 v[90:91], v[90:91], v[206:207]
	v_pk_mul_f32 v[96:97], v[96:97], v[92:93]
	v_pk_mul_f32 v[98:99], v[98:99], v[94:95]
	v_pk_mul_f32 v[88:89], v[88:89], v[84:85]
	v_pk_mul_f32 v[90:91], v[90:91], v[86:87]
	v_cvt_pk_bf16_f32 v208, v96, v97
	v_cvt_pk_bf16_f32 v209, v98, v99
	v_cvt_pk_bf16_f32 v210, v88, v89
	v_cvt_pk_bf16_f32 v211, v90, v91
	global_store_dwordx4 v213, v[208:211], s[66:67]
	v_pk_mul_f32 v[80:81], v[80:81], v[222:223] op_sel_hi:[1,0]
	v_pk_mul_f32 v[82:83], v[82:83], v[222:223] op_sel_hi:[1,0]
	v_pk_mul_f32 v[72:73], v[72:73], v[222:223] op_sel_hi:[1,0]
	v_pk_mul_f32 v[74:75], v[74:75], v[222:223] op_sel_hi:[1,0]
	v_pk_mul_f32 v[76:77], v[76:77], v[222:223] op_sel_hi:[1,0]
	v_pk_mul_f32 v[78:79], v[78:79], v[222:223] op_sel_hi:[1,0]
	v_pk_mul_f32 v[68:69], v[68:69], v[222:223] op_sel_hi:[1,0]
	v_pk_mul_f32 v[70:71], v[70:71], v[222:223] op_sel_hi:[1,0]
	v_pk_mul_f32 v[200:201], v[80:81], v[154:155] op_sel_hi:[1,0]
	v_pk_mul_f32 v[202:203], v[82:83], v[154:155] op_sel_hi:[1,0]
	v_pk_mul_f32 v[204:205], v[72:73], v[154:155] op_sel_hi:[1,0]
	v_pk_mul_f32 v[206:207], v[74:75], v[154:155] op_sel_hi:[1,0]
	v_exp_f32_e32 v200, v200
	v_exp_f32_e32 v201, v201
	v_exp_f32_e32 v202, v202
	v_exp_f32_e32 v203, v203
	v_exp_f32_e32 v204, v204
	v_exp_f32_e32 v205, v205
	v_exp_f32_e32 v206, v206
	v_exp_f32_e32 v207, v207
	v_pk_add_f32 v[200:201], v[200:201], v[156:157] op_sel_hi:[1,0]
	v_pk_add_f32 v[202:203], v[202:203], v[156:157] op_sel_hi:[1,0]
	v_pk_add_f32 v[204:205], v[204:205], v[156:157] op_sel_hi:[1,0]
	v_pk_add_f32 v[206:207], v[206:207], v[156:157] op_sel_hi:[1,0]
	v_rcp_f32_e32 v200, v200
	v_rcp_f32_e32 v201, v201
	v_rcp_f32_e32 v202, v202
	v_rcp_f32_e32 v203, v203
	v_rcp_f32_e32 v204, v204
	v_rcp_f32_e32 v205, v205
	v_rcp_f32_e32 v206, v206
	v_rcp_f32_e32 v207, v207
	v_pk_mul_f32 v[80:81], v[80:81], v[200:201]
	v_pk_mul_f32 v[82:83], v[82:83], v[202:203]
	v_pk_mul_f32 v[72:73], v[72:73], v[204:205]
	v_pk_mul_f32 v[74:75], v[74:75], v[206:207]
	v_pk_mul_f32 v[80:81], v[80:81], v[76:77]
	v_pk_mul_f32 v[82:83], v[82:83], v[78:79]
	v_pk_mul_f32 v[72:73], v[72:73], v[68:69]
	v_pk_mul_f32 v[74:75], v[74:75], v[70:71]
	v_cvt_pk_bf16_f32 v208, v80, v81
	v_cvt_pk_bf16_f32 v209, v82, v83
	v_cvt_pk_bf16_f32 v210, v72, v73
	v_cvt_pk_bf16_f32 v211, v74, v75
	global_store_dwordx4 v213, v[208:211], s[66:67] offset:2048
	v_pk_mul_f32 v[64:65], v[64:65], v[224:225] op_sel_hi:[1,0]
	v_pk_mul_f32 v[66:67], v[66:67], v[224:225] op_sel_hi:[1,0]
	v_pk_mul_f32 v[56:57], v[56:57], v[224:225] op_sel_hi:[1,0]
	v_pk_mul_f32 v[58:59], v[58:59], v[224:225] op_sel_hi:[1,0]
	v_pk_mul_f32 v[60:61], v[60:61], v[224:225] op_sel_hi:[1,0]
	v_pk_mul_f32 v[62:63], v[62:63], v[224:225] op_sel_hi:[1,0]
	v_pk_mul_f32 v[52:53], v[52:53], v[224:225] op_sel_hi:[1,0]
	v_pk_mul_f32 v[54:55], v[54:55], v[224:225] op_sel_hi:[1,0]
	v_pk_mul_f32 v[200:201], v[64:65], v[154:155] op_sel_hi:[1,0]
	v_pk_mul_f32 v[202:203], v[66:67], v[154:155] op_sel_hi:[1,0]
	v_pk_mul_f32 v[204:205], v[56:57], v[154:155] op_sel_hi:[1,0]
	v_pk_mul_f32 v[206:207], v[58:59], v[154:155] op_sel_hi:[1,0]
	v_exp_f32_e32 v200, v200
	v_exp_f32_e32 v201, v201
	v_exp_f32_e32 v202, v202
	v_exp_f32_e32 v203, v203
	v_exp_f32_e32 v204, v204
	v_exp_f32_e32 v205, v205
	v_exp_f32_e32 v206, v206
	v_exp_f32_e32 v207, v207
	v_pk_add_f32 v[200:201], v[200:201], v[156:157] op_sel_hi:[1,0]
	v_pk_add_f32 v[202:203], v[202:203], v[156:157] op_sel_hi:[1,0]
	v_pk_add_f32 v[204:205], v[204:205], v[156:157] op_sel_hi:[1,0]
	v_pk_add_f32 v[206:207], v[206:207], v[156:157] op_sel_hi:[1,0]
	v_rcp_f32_e32 v200, v200
	v_rcp_f32_e32 v201, v201
	v_rcp_f32_e32 v202, v202
	v_rcp_f32_e32 v203, v203
	v_rcp_f32_e32 v204, v204
	v_rcp_f32_e32 v205, v205
	v_rcp_f32_e32 v206, v206
	v_rcp_f32_e32 v207, v207
	v_pk_mul_f32 v[64:65], v[64:65], v[200:201]
	v_pk_mul_f32 v[66:67], v[66:67], v[202:203]
	v_pk_mul_f32 v[56:57], v[56:57], v[204:205]
	v_pk_mul_f32 v[58:59], v[58:59], v[206:207]
	v_pk_mul_f32 v[64:65], v[64:65], v[60:61]
	v_pk_mul_f32 v[66:67], v[66:67], v[62:63]
	v_pk_mul_f32 v[56:57], v[56:57], v[52:53]
	v_pk_mul_f32 v[58:59], v[58:59], v[54:55]
	v_cvt_pk_bf16_f32 v208, v64, v65
	v_cvt_pk_bf16_f32 v209, v66, v67
	v_cvt_pk_bf16_f32 v210, v56, v57
	v_cvt_pk_bf16_f32 v211, v58, v59
	global_store_dwordx4 v214, v[208:211], s[66:67]
	v_pk_mul_f32 v[48:49], v[48:49], v[226:227] op_sel_hi:[1,0]
	v_pk_mul_f32 v[50:51], v[50:51], v[226:227] op_sel_hi:[1,0]
	v_pk_mul_f32 v[40:41], v[40:41], v[226:227] op_sel_hi:[1,0]
	v_pk_mul_f32 v[42:43], v[42:43], v[226:227] op_sel_hi:[1,0]
	v_pk_mul_f32 v[44:45], v[44:45], v[226:227] op_sel_hi:[1,0]
	v_pk_mul_f32 v[46:47], v[46:47], v[226:227] op_sel_hi:[1,0]
	v_pk_mul_f32 v[36:37], v[36:37], v[226:227] op_sel_hi:[1,0]
	v_pk_mul_f32 v[38:39], v[38:39], v[226:227] op_sel_hi:[1,0]
	v_pk_mul_f32 v[200:201], v[48:49], v[154:155] op_sel_hi:[1,0]
	v_pk_mul_f32 v[202:203], v[50:51], v[154:155] op_sel_hi:[1,0]
	v_pk_mul_f32 v[204:205], v[40:41], v[154:155] op_sel_hi:[1,0]
	v_pk_mul_f32 v[206:207], v[42:43], v[154:155] op_sel_hi:[1,0]
	v_exp_f32_e32 v200, v200
	v_exp_f32_e32 v201, v201
	v_exp_f32_e32 v202, v202
	v_exp_f32_e32 v203, v203
	v_exp_f32_e32 v204, v204
	v_exp_f32_e32 v205, v205
	v_exp_f32_e32 v206, v206
	v_exp_f32_e32 v207, v207
	v_pk_add_f32 v[200:201], v[200:201], v[156:157] op_sel_hi:[1,0]
	v_pk_add_f32 v[202:203], v[202:203], v[156:157] op_sel_hi:[1,0]
	v_pk_add_f32 v[204:205], v[204:205], v[156:157] op_sel_hi:[1,0]
	v_pk_add_f32 v[206:207], v[206:207], v[156:157] op_sel_hi:[1,0]
	v_rcp_f32_e32 v200, v200
	v_rcp_f32_e32 v201, v201
	v_rcp_f32_e32 v202, v202
	v_rcp_f32_e32 v203, v203
	v_rcp_f32_e32 v204, v204
	v_rcp_f32_e32 v205, v205
	v_rcp_f32_e32 v206, v206
	v_rcp_f32_e32 v207, v207
	v_pk_mul_f32 v[48:49], v[48:49], v[200:201]
	v_pk_mul_f32 v[50:51], v[50:51], v[202:203]
	v_pk_mul_f32 v[40:41], v[40:41], v[204:205]
	v_pk_mul_f32 v[42:43], v[42:43], v[206:207]
	v_pk_mul_f32 v[48:49], v[48:49], v[44:45]
	v_pk_mul_f32 v[50:51], v[50:51], v[46:47]
	v_pk_mul_f32 v[40:41], v[40:41], v[36:37]
	v_pk_mul_f32 v[42:43], v[42:43], v[38:39]
	v_cvt_pk_bf16_f32 v208, v48, v49
	v_cvt_pk_bf16_f32 v209, v50, v51
	v_cvt_pk_bf16_f32 v210, v40, v41
	v_cvt_pk_bf16_f32 v211, v42, v43
	global_store_dwordx4 v214, v[208:211], s[66:67] offset:2048
	v_pk_mul_f32 v[32:33], v[32:33], v[228:229] op_sel_hi:[1,0]
	v_pk_mul_f32 v[34:35], v[34:35], v[228:229] op_sel_hi:[1,0]
	v_pk_mul_f32 v[24:25], v[24:25], v[228:229] op_sel_hi:[1,0]
	v_pk_mul_f32 v[26:27], v[26:27], v[228:229] op_sel_hi:[1,0]
	v_pk_mul_f32 v[28:29], v[28:29], v[228:229] op_sel_hi:[1,0]
	v_pk_mul_f32 v[30:31], v[30:31], v[228:229] op_sel_hi:[1,0]
	v_pk_mul_f32 v[20:21], v[20:21], v[228:229] op_sel_hi:[1,0]
	v_pk_mul_f32 v[22:23], v[22:23], v[228:229] op_sel_hi:[1,0]
	v_pk_mul_f32 v[200:201], v[32:33], v[154:155] op_sel_hi:[1,0]
	v_pk_mul_f32 v[202:203], v[34:35], v[154:155] op_sel_hi:[1,0]
	v_pk_mul_f32 v[204:205], v[24:25], v[154:155] op_sel_hi:[1,0]
	v_pk_mul_f32 v[206:207], v[26:27], v[154:155] op_sel_hi:[1,0]
	v_exp_f32_e32 v200, v200
	v_exp_f32_e32 v201, v201
	v_exp_f32_e32 v202, v202
	v_exp_f32_e32 v203, v203
	v_exp_f32_e32 v204, v204
	v_exp_f32_e32 v205, v205
	v_exp_f32_e32 v206, v206
	v_exp_f32_e32 v207, v207
	v_pk_add_f32 v[200:201], v[200:201], v[156:157] op_sel_hi:[1,0]
	v_pk_add_f32 v[202:203], v[202:203], v[156:157] op_sel_hi:[1,0]
	v_pk_add_f32 v[204:205], v[204:205], v[156:157] op_sel_hi:[1,0]
	v_pk_add_f32 v[206:207], v[206:207], v[156:157] op_sel_hi:[1,0]
	v_rcp_f32_e32 v200, v200
	v_rcp_f32_e32 v201, v201
	v_rcp_f32_e32 v202, v202
	v_rcp_f32_e32 v203, v203
	v_rcp_f32_e32 v204, v204
	v_rcp_f32_e32 v205, v205
	v_rcp_f32_e32 v206, v206
	v_rcp_f32_e32 v207, v207
	v_pk_mul_f32 v[32:33], v[32:33], v[200:201]
	v_pk_mul_f32 v[34:35], v[34:35], v[202:203]
	v_pk_mul_f32 v[24:25], v[24:25], v[204:205]
	v_pk_mul_f32 v[26:27], v[26:27], v[206:207]
	v_pk_mul_f32 v[32:33], v[32:33], v[28:29]
	v_pk_mul_f32 v[34:35], v[34:35], v[30:31]
	v_pk_mul_f32 v[24:25], v[24:25], v[20:21]
	v_pk_mul_f32 v[26:27], v[26:27], v[22:23]
	v_cvt_pk_bf16_f32 v208, v32, v33
	v_cvt_pk_bf16_f32 v209, v34, v35
	v_cvt_pk_bf16_f32 v210, v24, v25
	v_cvt_pk_bf16_f32 v211, v26, v27
	global_store_dwordx4 v215, v[208:211], s[66:67]
	v_pk_mul_f32 v[16:17], v[16:17], v[230:231] op_sel_hi:[1,0]
	v_pk_mul_f32 v[18:19], v[18:19], v[230:231] op_sel_hi:[1,0]
	v_pk_mul_f32 v[8:9], v[8:9], v[230:231] op_sel_hi:[1,0]
	v_pk_mul_f32 v[10:11], v[10:11], v[230:231] op_sel_hi:[1,0]
	v_pk_mul_f32 v[12:13], v[12:13], v[230:231] op_sel_hi:[1,0]
	v_pk_mul_f32 v[14:15], v[14:15], v[230:231] op_sel_hi:[1,0]
	v_pk_mul_f32 v[4:5], v[4:5], v[230:231] op_sel_hi:[1,0]
	v_pk_mul_f32 v[6:7], v[6:7], v[230:231] op_sel_hi:[1,0]
	v_pk_mul_f32 v[200:201], v[16:17], v[154:155] op_sel_hi:[1,0]
	v_pk_mul_f32 v[202:203], v[18:19], v[154:155] op_sel_hi:[1,0]
	v_pk_mul_f32 v[204:205], v[8:9], v[154:155] op_sel_hi:[1,0]
	v_pk_mul_f32 v[206:207], v[10:11], v[154:155] op_sel_hi:[1,0]
	v_exp_f32_e32 v200, v200
	v_exp_f32_e32 v201, v201
	v_exp_f32_e32 v202, v202
	v_exp_f32_e32 v203, v203
	v_exp_f32_e32 v204, v204
	v_exp_f32_e32 v205, v205
	v_exp_f32_e32 v206, v206
	v_exp_f32_e32 v207, v207
	v_pk_add_f32 v[200:201], v[200:201], v[156:157] op_sel_hi:[1,0]
	v_pk_add_f32 v[202:203], v[202:203], v[156:157] op_sel_hi:[1,0]
	v_pk_add_f32 v[204:205], v[204:205], v[156:157] op_sel_hi:[1,0]
	v_pk_add_f32 v[206:207], v[206:207], v[156:157] op_sel_hi:[1,0]
	v_rcp_f32_e32 v200, v200
	v_rcp_f32_e32 v201, v201
	v_rcp_f32_e32 v202, v202
	v_rcp_f32_e32 v203, v203
	v_rcp_f32_e32 v204, v204
	v_rcp_f32_e32 v205, v205
	v_rcp_f32_e32 v206, v206
	v_rcp_f32_e32 v207, v207
	v_pk_mul_f32 v[16:17], v[16:17], v[200:201]
	v_pk_mul_f32 v[18:19], v[18:19], v[202:203]
	v_pk_mul_f32 v[8:9], v[8:9], v[204:205]
	v_pk_mul_f32 v[10:11], v[10:11], v[206:207]
	v_pk_mul_f32 v[16:17], v[16:17], v[12:13]
	v_pk_mul_f32 v[18:19], v[18:19], v[14:15]
	v_pk_mul_f32 v[8:9], v[8:9], v[4:5]
	v_pk_mul_f32 v[10:11], v[10:11], v[6:7]
	v_cvt_pk_bf16_f32 v208, v16, v17
	v_cvt_pk_bf16_f32 v209, v18, v19
	v_cvt_pk_bf16_f32 v210, v8, v9
	v_cvt_pk_bf16_f32 v211, v10, v11
	global_store_dwordx4 v215, v[208:211], s[66:67] offset:2048
	s_mov_b64 s[14:15], -1
	s_andn2_b64 vcc, exec, s[12:13]
	s_branch .Lp4_epi_tail

.Lp4_epi_tail:
	s_cbranch_vccnz .LBB0_660
	s_andn2_b64 vcc, exec, s[2:3]
	s_cbranch_vccnz .LBB0_659
	s_barrier
	s_branch .LBB0_659
